# speedup vs baseline: 1.0107x; 1.0007x over previous
; template <typename SrcF, typename PostF>
; __device__ __forceinline__ void gemm_stream32(const int nt, SrcF src32, PostF post32, f32x4 (&acc)[4][4], char* smem) {
;     ...
;   __syncthreads();
;   G_LOAD(g0, 0);
;   G_LOAD(g1, 1);
;   G_WRITE(g0, 0);
;   G_LOAD(g0, 2);
;   __syncthreads();
; __device__ void phase_merge(const Params& p, int layer, char* smem) {
;     ...
;   for (int t = li_; t < rbp_ * 8; t += nl_) {
;     const int rg_ = t / (8 * 8), v_ = t % (8 * 8);
;     const int rb = xg_ * rbp_ + rg_ * 8 + (v_ & 7), cb = v_ >> 3;
;     f32x4 mg[4][4], acc[4][4];
; #pragma unroll
;     for (int m = 0; m < 4; ++m)
; #pragma unroll
;       for (int n = 0; n < 4; ++n) {
;         mg[m][n] = f32x4{0.f, 0.f, 0.f, 0.f};
;         acc[m][n] = f32x4{0.f, 0.f, 0.f, 0.f};
;       }
;     const u16* Hb = H + (size_t)rb * 128 * 1024;
;     const u16* Wg = Wt + (size_t)(NP + cb * 128) * 1024;
;     const u16* Yb = Y + (size_t)rb * 128 * YW;
;     const u16* Wb = Wbr + (size_t)(cb * 128) * 512;
;     const float* bmp = p.b_merge + (size_t)layer * 3072 + cb * 128 + wc * 64 + fr;
.LBB0_258:
	s_ashr_i32 s4, s66, 31
	s_lshr_b32 s4, s4, 26
	s_add_i32 s4, s66, s4
	s_ashr_i32 s5, s4, 6
	s_andn2_b32 s4, s4, 63
	s_sub_i32 s8, s66, s4
	s_lshl_b32 s4, s5, 3
	s_and_b32 s5, s8, 7
	s_add_i32 s4, s4, s53
	s_add_i32 s4, s4, s5
	s_ashr_i32 s5, s4, 31
	v_mov_b32_e32 v36, v232
	s_lshl_b64 s[24:25], s[4:5], 17
	s_lshl_b64 s[6:7], s[4:5], 18
	s_add_u32 s26, s42, s6
	v_lshrrev_b32_e32 v1, 4, v36
	v_lshrrev_b32_e32 v2, 5, v36
	v_xor_b32_e32 v1, v1, v2
	s_addc_u32 s27, s43, s7
	s_lshl_b32 s5, s8, 4
	v_lshlrev_b32_e32 v1, 1, v1
	s_and_b32 s36, s5, 0xffffff80
	v_ashrrev_i32_e32 v235, 2, v36
	v_and_b32_e32 v37, 3, v36
	v_bfe_u32 v3, v36, 5, 1
	v_and_b32_e32 v1, 2, v1
	s_add_i32 s14, s36, 0x1300
	v_bitop3_b32 v38, v1, v37, v3 bitop3:0x36
	v_lshlrev_b32_e32 v1, 11, v235
	s_lshl_b64 s[6:7], s[14:15], 11
	v_lshl_or_b32 v39, v38, 4, v1
	s_add_u32 s38, s44, s6
	v_add_u32_e32 v40, 0x20000, v39
	s_addc_u32 s39, s45, s7
	s_barrier
	global_load_dwordx4 v[20:23], v39, s[26:27]
	global_load_dwordx4 v[24:27], v40, s[26:27]
	global_load_dwordx4 v[28:31], v39, s[38:39]
	global_load_dwordx4 v[32:35], v40, s[38:39]
	global_load_dwordx4 v[68:71], v39, s[26:27] offset:64
	global_load_dwordx4 v[72:75], v40, s[26:27] offset:64
	global_load_dwordx4 v[84:87], v39, s[38:39] offset:64
	global_load_dwordx4 v[92:95], v40, s[38:39] offset:64
	global_load_dwordx4 v[76:79], v39, s[26:27] offset:128
	global_load_dwordx4 v[80:83], v40, s[26:27] offset:128
	global_load_dwordx4 v[88:91], v39, s[38:39] offset:128
	global_load_dwordx4 v[96:99], v40, s[38:39] offset:128
	v_lshrrev_b32_e32 v42, 2, v36
	v_bfe_u32 v43, v36, 3, 1
	s_mul_hi_i32 s5, s4, 0x60000
	s_mul_i32 s4, s4, 0x60000
	v_and_b32_e32 v41, 15, v36
	v_lshrrev_b32_e32 v45, 1, v36
	v_lshlrev_b32_e32 v37, 4, v37
	v_bitop3_b32 v42, v42, v43, 1 bitop3:0x6c
	s_add_u32 s69, s49, s4
	v_and_b32_e32 v44, 48, v36
	v_lshlrev_b32_e32 v43, 4, v43
	v_and_or_b32 v41, v45, s54, v41
	v_lshl_or_b32 v236, v235, 6, v37
	v_lshlrev_b32_e32 v37, 5, v42
	s_addc_u32 s70, s50, s5
	s_ashr_i32 s37, s36, 31
	v_mov_b32_e32 v2, v0
	v_mov_b32_e32 v3, v0
	v_mov_b32_e32 v6, v0
	v_mov_b32_e32 v7, v0
	v_lshlrev_b32_e32 v36, 6, v36
	v_lshlrev_b32_e32 v41, 6, v41
	v_or_b32_e32 v42, v37, v43
	v_bitop3_b32 v37, v37, v44, v43 bitop3:0x36
	s_lshl_b64 s[4:5], s[36:37], 10
	v_mov_b32_e32 v1, v0
	v_mov_b32_e32 v4, v0
	v_mov_b32_e32 v5, v0
	v_mov_b32_e32 v100, 0
	v_mov_b64_e32 v[10:11], v[6:7]
	v_mov_b64_e32 v[14:15], v[6:7]
	v_mov_b64_e32 v[18:19], v[6:7]
	v_bitop3_b32 v237, v42, v41, v44 bitop3:0xde
	v_and_or_b32 v238, v36, s55, v37
	v_lshlrev_b32_e32 v239, 3, v38
	s_add_u32 s40, s46, s4
	v_mov_b64_e32 v[38:39], v[6:7]
	v_mov_b64_e32 v[42:43], v[6:7]
	v_mov_b64_e32 v[46:47], v[6:7]
	v_mov_b64_e32 v[50:51], v[6:7]
	v_mov_b64_e32 v[54:55], v[6:7]
	v_mov_b64_e32 v[58:59], v[6:7]
	v_mov_b64_e32 v[62:63], v[6:7]
	v_mov_b64_e32 v[66:67], v[6:7]
	v_mov_b64_e32 v[106:107], v[2:3]
	s_mov_b32 s67, -2
	s_mov_b32 s68, 1
	v_mov_b64_e32 v[8:9], v[4:5]
	v_mov_b64_e32 v[12:13], v[4:5]
	v_mov_b64_e32 v[16:17], v[4:5]
	v_lshl_add_u64 v[230:231], s[36:37], 2, v[228:229]
	s_addc_u32 s41, s48, s5
	v_mov_b64_e32 v[36:37], v[4:5]
	s_waitcnt vmcnt(11)
	ds_write_b128 v236, v[20:23]
	s_waitcnt vmcnt(10)
	ds_write_b128 v236, v[24:27] offset:4096
	s_waitcnt vmcnt(9)
	ds_write_b128 v236, v[28:31] offset:8192
	s_waitcnt vmcnt(8)
	ds_write_b128 v236, v[32:35] offset:12288
	v_mov_b64_e32 v[22:23], v[6:7]
	v_mov_b64_e32 v[26:27], v[6:7]
	v_mov_b64_e32 v[30:31], v[6:7]
	v_mov_b64_e32 v[34:35], v[6:7]
	v_mov_b64_e32 v[20:21], v[4:5]
	v_mov_b64_e32 v[24:25], v[4:5]
	v_mov_b64_e32 v[28:29], v[4:5]
	v_mov_b64_e32 v[32:33], v[4:5]
	v_mov_b64_e32 v[40:41], v[4:5]
	v_mov_b64_e32 v[44:45], v[4:5]
	v_mov_b64_e32 v[48:49], v[4:5]
	v_mov_b64_e32 v[52:53], v[4:5]
	v_mov_b64_e32 v[56:57], v[4:5]
	v_mov_b64_e32 v[60:61], v[4:5]
	v_mov_b64_e32 v[64:65], v[4:5]
	v_mov_b64_e32 v[104:105], v[0:1]
	v_mov_b32_e32 v101, v100
	v_mov_b32_e32 v102, v100
	v_mov_b32_e32 v103, v100
	v_mov_b32_e32 v108, v100
	v_mov_b32_e32 v109, v100
	v_mov_b32_e32 v110, v100
	v_mov_b32_e32 v111, v100
	v_mov_b32_e32 v112, v100
	v_mov_b32_e32 v113, v100
	v_mov_b32_e32 v114, v100
	v_mov_b32_e32 v115, v100
	v_mov_b32_e32 v116, v100
	v_mov_b32_e32 v117, v100
	v_mov_b32_e32 v118, v100
	v_mov_b32_e32 v119, v100
	v_mov_b32_e32 v120, v100
	v_mov_b32_e32 v121, v100
	v_mov_b32_e32 v122, v100
	v_mov_b32_e32 v123, v100
	v_mov_b32_e32 v124, v100
	v_mov_b32_e32 v125, v100
	v_mov_b32_e32 v126, v100
	v_mov_b32_e32 v127, v100
	v_mov_b32_e32 v128, v100
	v_mov_b32_e32 v129, v100
	v_mov_b32_e32 v130, v100
	v_mov_b32_e32 v131, v100
	v_mov_b32_e32 v132, v100
	v_mov_b32_e32 v133, v100
	v_mov_b32_e32 v134, v100
	v_mov_b32_e32 v135, v100
	v_mov_b32_e32 v136, v100
	v_mov_b32_e32 v137, v100
	v_mov_b32_e32 v138, v100
	v_mov_b32_e32 v139, v100
	v_mov_b32_e32 v140, v100
	v_mov_b32_e32 v141, v100
	v_mov_b32_e32 v142, v100
	v_mov_b32_e32 v143, v100
	v_mov_b32_e32 v144, v100
	v_mov_b32_e32 v145, v100
	v_mov_b32_e32 v146, v100
	v_mov_b32_e32 v147, v100
	v_mov_b32_e32 v148, v100
	v_mov_b32_e32 v149, v100
	v_mov_b32_e32 v150, v100
	v_mov_b32_e32 v151, v100
	v_mov_b32_e32 v152, v100
	v_mov_b32_e32 v153, v100
	v_mov_b32_e32 v154, v100
	v_mov_b32_e32 v155, v100
	v_mov_b32_e32 v156, v100
	v_mov_b32_e32 v157, v100
	v_mov_b32_e32 v158, v100
	v_mov_b32_e32 v159, v100
	v_mov_b32_e32 v160, v100
	v_mov_b32_e32 v161, v100
	v_mov_b32_e32 v162, v100
	v_mov_b32_e32 v163, v100
	s_waitcnt lgkmcnt(0)
	s_barrier
	s_branch .LBB0_260

.LBB0_260:
	ds_read_b128 v[164:167], v237
	ds_read_b128 v[168:171], v238 offset:8192
	ds_read_b128 v[172:175], v238 offset:9216
	ds_read_b128 v[176:179], v237 offset:1024
	ds_read_b128 v[180:183], v238 offset:10240
	ds_read_b128 v[184:187], v238 offset:11264
	s_add_i32 s67, s67, 2
	s_min_u32 s74, s67, 0x8c
	s_add_i32 s74, s74, 3
	s_mul_i32 s75, s74, 0xab
	s_bfe_u32 s75, s75, 0x3000d
	s_mul_i32 s76, s75, 0xffffffd0
	s_add_i32 s76, s76, s74
	s_movk_i32 s77, 0x400
	s_movk_i32 s78, 0x400
	s_cmp_gt_i32 s76, 31
	s_cselect_b32 s77, 0x600, s77
	s_cselect_b32 s78, 0x200, s78
	s_cselect_b32 s79, 20, 21
	s_cselect_b32 s80, s69, s26
	s_cselect_b32 s81, s70, s27
	s_cselect_b32 s82, s40, s38
	s_cselect_b32 s83, s41, s39
	s_cselect_b32 s84, 32, 0
	s_cselect_b32 s85, s75, 0
	s_sub_i32 s76, s76, s84
	s_lshl_b32 s76, s76, 6
	s_lshl_b32 s85, s85, 10
	s_add_u32 s80, s80, s85
	s_addc_u32 s81, s81, 0
	s_add_u32 s80, s80, s76
	s_addc_u32 s81, s81, 0
	s_lshl_b32 s75, s75, s79
	s_add_u32 s82, s82, s75
	s_addc_u32 s83, s83, 0
	s_add_u32 s82, s82, s76
	s_addc_u32 s83, s83, 0
	v_mul_lo_u32 v1, s77, v235
	v_mul_lo_u32 v2, s78, v235
	v_or_b32_e32 v1, v1, v239
	v_or_b32_e32 v2, v2, v239
	v_lshlrev_b32_e32 v1, 1, v1
	v_lshlrev_b32_e32 v2, 1, v2
	v_lshl_add_u32 v3, s77, 7, v1
	v_lshl_add_u32 v188, s78, 7, v2
	s_waitcnt lgkmcnt(4)
	v_mfma_f32_16x16x32_bf16 v[160:163], v[164:167], v[168:171], v[160:163]
	s_waitcnt lgkmcnt(3)
	v_mfma_f32_16x16x32_bf16 v[156:159], v[164:167], v[172:175], v[156:159]
	s_waitcnt lgkmcnt(1)
	v_mfma_f32_16x16x32_bf16 v[152:155], v[164:167], v[180:183], v[152:155]
	s_waitcnt lgkmcnt(0)
	v_mfma_f32_16x16x32_bf16 v[148:151], v[164:167], v[184:187], v[148:151]
	ds_read_b128 v[164:167], v237 offset:2048
	v_mfma_f32_16x16x32_bf16 v[144:147], v[176:179], v[168:171], v[144:147]
	s_waitcnt vmcnt(7)
	ds_write_b128 v236, v[68:71] offset:16384
	global_load_dwordx4 v[68:71], v1, s[80:81]
	v_mfma_f32_16x16x32_bf16 v[140:143], v[176:179], v[172:175], v[140:143]
	s_waitcnt vmcnt(7)
	ds_write_b128 v236, v[72:75] offset:20480
	global_load_dwordx4 v[72:75], v3, s[80:81]
	v_mfma_f32_16x16x32_bf16 v[136:139], v[176:179], v[180:183], v[136:139]
	s_waitcnt vmcnt(7)
	ds_write_b128 v236, v[84:87] offset:24576
	global_load_dwordx4 v[84:87], v2, s[82:83]
	v_mfma_f32_16x16x32_bf16 v[132:135], v[176:179], v[184:187], v[132:135]
	s_waitcnt vmcnt(7)
	ds_write_b128 v236, v[92:95] offset:28672
	global_load_dwordx4 v[92:95], v188, s[82:83]
	ds_read_b128 v[176:179], v237 offset:3072
	s_waitcnt lgkmcnt(5)
	v_mfma_f32_16x16x32_bf16 v[128:131], v[164:167], v[168:171], v[128:131]
	v_mfma_f32_16x16x32_bf16 v[124:127], v[164:167], v[172:175], v[124:127]
	v_mfma_f32_16x16x32_bf16 v[120:123], v[164:167], v[180:183], v[120:123]
	v_mfma_f32_16x16x32_bf16 v[116:119], v[164:167], v[184:187], v[116:119]
	s_waitcnt lgkmcnt(0)
	v_mfma_f32_16x16x32_bf16 v[112:115], v[176:179], v[168:171], v[112:115]
	v_mfma_f32_16x16x32_bf16 v[108:111], v[176:179], v[172:175], v[108:111]
	v_mfma_f32_16x16x32_bf16 v[100:103], v[176:179], v[180:183], v[100:103]
	v_mfma_f32_16x16x32_bf16 v[104:107], v[176:179], v[184:187], v[104:107]
	s_waitcnt lgkmcnt(0)
	s_barrier
	ds_read_b128 v[164:167], v237 offset:16384
	ds_read_b128 v[176:179], v237 offset:17408
	ds_read_b128 v[168:171], v238 offset:24576
	ds_read_b128 v[172:175], v238 offset:25600
	ds_read_b128 v[180:183], v238 offset:26624
	ds_read_b128 v[184:187], v238 offset:27648
	s_waitcnt lgkmcnt(3)
	v_mfma_f32_16x16x32_bf16 v[160:163], v[164:167], v[168:171], v[160:163]
	s_min_u32 s4, s67, 0x8b
	s_add_i32 s4, s4, 4
	s_mul_i32 s5, s4, 0xab
	s_waitcnt lgkmcnt(2)
	v_mfma_f32_16x16x32_bf16 v[156:159], v[164:167], v[172:175], v[156:159]
	s_bfe_u32 s71, s5, 0x3000d
	s_mul_i32 s10, s71, 0xffffffd0
	s_add_i32 s10, s10, s4
	s_waitcnt lgkmcnt(1)
	v_mfma_f32_16x16x32_bf16 v[152:155], v[164:167], v[180:183], v[152:155]
	s_mov_b64 s[8:9], -1
	s_cmp_gt_i32 s10, 31
	s_waitcnt lgkmcnt(0)
	v_mfma_f32_16x16x32_bf16 v[148:151], v[164:167], v[184:187], v[148:151]
	ds_read_b128 v[164:167], v237 offset:18432
	v_mfma_f32_16x16x32_bf16 v[144:147], v[176:179], v[168:171], v[144:147]
	v_mfma_f32_16x16x32_bf16 v[140:143], v[176:179], v[172:175], v[140:143]
	v_mfma_f32_16x16x32_bf16 v[136:139], v[176:179], v[180:183], v[136:139]
	v_mfma_f32_16x16x32_bf16 v[132:135], v[176:179], v[184:187], v[132:135]
	ds_read_b128 v[176:179], v237 offset:19456
	s_waitcnt vmcnt(7)
	ds_write_b128 v236, v[76:79]
	s_waitcnt vmcnt(6)
	ds_write_b128 v236, v[80:83] offset:4096
	s_waitcnt lgkmcnt(3)
	v_mfma_f32_16x16x32_bf16 v[128:131], v[164:167], v[168:171], v[128:131]
	s_waitcnt vmcnt(5)
	ds_write_b128 v236, v[88:91] offset:8192
	s_waitcnt vmcnt(4)
	ds_write_b128 v236, v[96:99] offset:12288
	v_mfma_f32_16x16x32_bf16 v[124:127], v[164:167], v[172:175], v[124:127]
	v_mfma_f32_16x16x32_bf16 v[120:123], v[164:167], v[180:183], v[120:123]
	v_mfma_f32_16x16x32_bf16 v[116:119], v[164:167], v[184:187], v[116:119]
	s_waitcnt lgkmcnt(4)
	v_mfma_f32_16x16x32_bf16 v[112:115], v[176:179], v[168:171], v[112:115]
	v_mfma_f32_16x16x32_bf16 v[108:111], v[176:179], v[172:175], v[108:111]
	v_mfma_f32_16x16x32_bf16 v[100:103], v[176:179], v[180:183], v[100:103]
	v_mfma_f32_16x16x32_bf16 v[104:107], v[176:179], v[184:187], v[104:107]
	s_cbranch_scc0 .LBB0_267
	s_lshl_b32 s4, s71, 10
	s_add_u32 s6, s69, s4
	s_addc_u32 s7, s70, 0
	s_lshl_b32 s4, s10, 5
	s_add_i32 s14, s4, 0xfffffc00
	s_lshl_b64 s[4:5], s[14:15], 1
	s_add_u32 s4, s6, s4
	s_addc_u32 s5, s7, s5
	s_mov_b64 s[8:9], 0
	s_mov_b64 s[6:7], s[14:15]

; template <typename SrcF, typename PostF>
; __device__ __forceinline__ void gemm_stream32(const int nt, SrcF src32, PostF post32, f32x4 (&acc)[4][4], char* smem) {
;     ...
;   __syncthreads();
;   G_LOAD(g0, 0);
;   G_LOAD(g1, 1);
;   G_WRITE(g0, 0);
;   G_LOAD(g0, 2);
;   __syncthreads();
; __device__ void phase_merge(const Params& p, int layer, char* smem) {
;     ...
;   for (int t = li_; t < rbp_ * 8; t += nl_) {
;     const int rg_ = t / (8 * 8), v_ = t % (8 * 8);
;     const int rb = xg_ * rbp_ + rg_ * 8 + (v_ & 7), cb = v_ >> 3;
;     f32x4 mg[4][4], acc[4][4];
; #pragma unroll
;     for (int m = 0; m < 4; ++m)
; #pragma unroll
;       for (int n = 0; n < 4; ++n) {
;         mg[m][n] = f32x4{0.f, 0.f, 0.f, 0.f};
;         acc[m][n] = f32x4{0.f, 0.f, 0.f, 0.f};
;       }
;     const u16* Hb = H + (size_t)rb * 128 * 1024;
;     const u16* Wg = Wt + (size_t)(NP + cb * 128) * 1024;
;     const u16* Yb = Y + (size_t)rb * 128 * YW;
;     const u16* Wb = Wbr + (size_t)(cb * 128) * 512;
;     const float* bmp = p.b_merge + (size_t)layer * 3072 + cb * 128 + wc * 64 + fr;
.LBB0_579:
	s_ashr_i32 s12, s66, 31
	s_lshr_b32 s12, s12, 26
	s_add_i32 s12, s66, s12
	s_ashr_i32 s13, s12, 6
	s_andn2_b32 s12, s12, 63
	s_sub_i32 s16, s66, s12
	s_lshl_b32 s12, s13, 3
	s_and_b32 s13, s16, 7
	s_add_i32 s12, s12, s53
	s_add_i32 s12, s12, s13
	s_ashr_i32 s13, s12, 31
	v_mov_b32_e32 v36, v232
	s_lshl_b64 s[24:25], s[12:13], 17
	s_lshl_b64 s[14:15], s[12:13], 18
	s_add_u32 s26, s42, s14
	v_lshrrev_b32_e32 v1, 4, v36
	v_lshrrev_b32_e32 v2, 5, v36
	v_xor_b32_e32 v1, v1, v2
	s_addc_u32 s27, s43, s15
	s_lshl_b32 s13, s16, 4
	v_lshlrev_b32_e32 v1, 1, v1
	s_and_b32 s36, s13, 0xffffff80
	v_ashrrev_i32_e32 v235, 2, v36
	v_and_b32_e32 v37, 3, v36
	v_bfe_u32 v3, v36, 5, 1
	v_and_b32_e32 v1, 2, v1
	s_add_i32 s22, s36, 0x1300
	v_bitop3_b32 v38, v1, v37, v3 bitop3:0x36
	v_lshlrev_b32_e32 v1, 11, v235
	s_lshl_b64 s[14:15], s[22:23], 11
	v_lshl_or_b32 v39, v38, 4, v1
	s_add_u32 s38, s44, s14
	v_add_u32_e32 v40, 0x20000, v39
	s_addc_u32 s39, s45, s15
	s_barrier
	global_load_dwordx4 v[20:23], v39, s[26:27]
	global_load_dwordx4 v[24:27], v40, s[26:27]
	global_load_dwordx4 v[28:31], v39, s[38:39]
	global_load_dwordx4 v[32:35], v40, s[38:39]
	global_load_dwordx4 v[68:71], v39, s[26:27] offset:64
	global_load_dwordx4 v[72:75], v40, s[26:27] offset:64
	global_load_dwordx4 v[84:87], v39, s[38:39] offset:64
	global_load_dwordx4 v[92:95], v40, s[38:39] offset:64
	global_load_dwordx4 v[76:79], v39, s[26:27] offset:128
	global_load_dwordx4 v[80:83], v40, s[26:27] offset:128
	global_load_dwordx4 v[88:91], v39, s[38:39] offset:128
	global_load_dwordx4 v[96:99], v40, s[38:39] offset:128
	v_lshrrev_b32_e32 v42, 2, v36
	v_bfe_u32 v43, v36, 3, 1
	s_mul_hi_i32 s13, s12, 0x60000
	s_mul_i32 s12, s12, 0x60000
	v_and_b32_e32 v41, 15, v36
	v_lshrrev_b32_e32 v45, 1, v36
	v_lshlrev_b32_e32 v37, 4, v37
	v_bitop3_b32 v42, v42, v43, 1 bitop3:0x6c
	s_add_u32 s69, s49, s12
	v_and_b32_e32 v44, 48, v36
	v_lshlrev_b32_e32 v43, 4, v43
	v_and_or_b32 v41, v45, s54, v41
	v_lshl_or_b32 v236, v235, 6, v37
	v_lshlrev_b32_e32 v37, 5, v42
	s_addc_u32 s70, s50, s13
	s_ashr_i32 s37, s36, 31
	v_mov_b32_e32 v2, v0
	v_mov_b32_e32 v3, v0
	v_mov_b32_e32 v6, v0
	v_mov_b32_e32 v7, v0
	v_lshlrev_b32_e32 v36, 6, v36
	v_lshlrev_b32_e32 v41, 6, v41
	v_or_b32_e32 v42, v37, v43
	v_bitop3_b32 v37, v37, v44, v43 bitop3:0x36
	s_lshl_b64 s[12:13], s[36:37], 10
	v_mov_b32_e32 v1, v0
	v_mov_b32_e32 v4, v0
	v_mov_b32_e32 v5, v0
	v_mov_b32_e32 v100, 0
	v_mov_b64_e32 v[10:11], v[6:7]
	v_mov_b64_e32 v[14:15], v[6:7]
	v_mov_b64_e32 v[18:19], v[6:7]
	v_bitop3_b32 v237, v42, v41, v44 bitop3:0xde
	v_and_or_b32 v238, v36, s55, v37
	v_lshlrev_b32_e32 v239, 3, v38
	s_add_u32 s40, s46, s12
	v_mov_b64_e32 v[38:39], v[6:7]
	v_mov_b64_e32 v[42:43], v[6:7]
	v_mov_b64_e32 v[46:47], v[6:7]
	v_mov_b64_e32 v[50:51], v[6:7]
	v_mov_b64_e32 v[54:55], v[6:7]
	v_mov_b64_e32 v[58:59], v[6:7]
	v_mov_b64_e32 v[62:63], v[6:7]
	v_mov_b64_e32 v[66:67], v[6:7]
	v_mov_b64_e32 v[106:107], v[2:3]
	s_mov_b32 s67, 1
	s_mov_b32 s68, -2
	v_mov_b64_e32 v[8:9], v[4:5]
	v_mov_b64_e32 v[12:13], v[4:5]
	v_mov_b64_e32 v[16:17], v[4:5]
	v_lshl_add_u64 v[230:231], s[36:37], 2, v[228:229]
	s_addc_u32 s41, s48, s13
	v_mov_b64_e32 v[36:37], v[4:5]
	s_waitcnt vmcnt(11)
	ds_write_b128 v236, v[20:23]
	s_waitcnt vmcnt(10)
	ds_write_b128 v236, v[24:27] offset:4096
	s_waitcnt vmcnt(9)
	ds_write_b128 v236, v[28:31] offset:8192
	s_waitcnt vmcnt(8)
	ds_write_b128 v236, v[32:35] offset:12288
	v_mov_b64_e32 v[22:23], v[6:7]
	v_mov_b64_e32 v[26:27], v[6:7]
	v_mov_b64_e32 v[30:31], v[6:7]
	v_mov_b64_e32 v[34:35], v[6:7]
	v_mov_b64_e32 v[20:21], v[4:5]
	v_mov_b64_e32 v[24:25], v[4:5]
	v_mov_b64_e32 v[28:29], v[4:5]
	v_mov_b64_e32 v[32:33], v[4:5]
	v_mov_b64_e32 v[40:41], v[4:5]
	v_mov_b64_e32 v[44:45], v[4:5]
	v_mov_b64_e32 v[48:49], v[4:5]
	v_mov_b64_e32 v[52:53], v[4:5]
	v_mov_b64_e32 v[56:57], v[4:5]
	v_mov_b64_e32 v[60:61], v[4:5]
	v_mov_b64_e32 v[64:65], v[4:5]
	v_mov_b64_e32 v[104:105], v[0:1]
	v_mov_b32_e32 v101, v100
	v_mov_b32_e32 v102, v100
	v_mov_b32_e32 v103, v100
	v_mov_b32_e32 v108, v100
	v_mov_b32_e32 v109, v100
	v_mov_b32_e32 v110, v100
	v_mov_b32_e32 v111, v100
	v_mov_b32_e32 v112, v100
	v_mov_b32_e32 v113, v100
	v_mov_b32_e32 v114, v100
	v_mov_b32_e32 v115, v100
	v_mov_b32_e32 v116, v100
	v_mov_b32_e32 v117, v100
	v_mov_b32_e32 v118, v100
	v_mov_b32_e32 v119, v100
	v_mov_b32_e32 v120, v100
	v_mov_b32_e32 v121, v100
	v_mov_b32_e32 v122, v100
	v_mov_b32_e32 v123, v100
	v_mov_b32_e32 v124, v100
	v_mov_b32_e32 v125, v100
	v_mov_b32_e32 v126, v100
	v_mov_b32_e32 v127, v100
	v_mov_b32_e32 v128, v100
	v_mov_b32_e32 v129, v100
	v_mov_b32_e32 v130, v100
	v_mov_b32_e32 v131, v100
	v_mov_b32_e32 v132, v100
	v_mov_b32_e32 v133, v100
	v_mov_b32_e32 v134, v100
	v_mov_b32_e32 v135, v100
	v_mov_b32_e32 v136, v100
	v_mov_b32_e32 v137, v100
	v_mov_b32_e32 v138, v100
	v_mov_b32_e32 v139, v100
	v_mov_b32_e32 v140, v100
	v_mov_b32_e32 v141, v100
	v_mov_b32_e32 v142, v100
	v_mov_b32_e32 v143, v100
	v_mov_b32_e32 v144, v100
	v_mov_b32_e32 v145, v100
	v_mov_b32_e32 v146, v100
	v_mov_b32_e32 v147, v100
	v_mov_b32_e32 v148, v100
	v_mov_b32_e32 v149, v100
	v_mov_b32_e32 v150, v100
	v_mov_b32_e32 v151, v100
	v_mov_b32_e32 v152, v100
	v_mov_b32_e32 v153, v100
	v_mov_b32_e32 v154, v100
	v_mov_b32_e32 v155, v100
	v_mov_b32_e32 v156, v100
	v_mov_b32_e32 v157, v100
	v_mov_b32_e32 v158, v100
	v_mov_b32_e32 v159, v100
	v_mov_b32_e32 v160, v100
	v_mov_b32_e32 v161, v100
	v_mov_b32_e32 v162, v100
	v_mov_b32_e32 v163, v100
	s_waitcnt lgkmcnt(0)
	s_barrier
	s_branch .LBB0_581

.LBB0_581:
	ds_read_b128 v[164:167], v237
	ds_read_b128 v[168:171], v238 offset:8192
	ds_read_b128 v[172:175], v238 offset:9216
	ds_read_b128 v[176:179], v237 offset:1024
	ds_read_b128 v[180:183], v238 offset:10240
	ds_read_b128 v[184:187], v238 offset:11264
	s_add_i32 s68, s68, 2
	s_min_u32 s74, s68, 0x8c
	s_add_i32 s74, s74, 3
	s_mul_i32 s75, s74, 0xab
	s_bfe_u32 s75, s75, 0x3000d
	s_mul_i32 s76, s75, 0xffffffd0
	s_add_i32 s76, s76, s74
	s_movk_i32 s77, 0x400
	s_movk_i32 s78, 0x400
	s_cmp_gt_i32 s76, 31
	s_cselect_b32 s77, 0x600, s77
	s_cselect_b32 s78, 0x200, s78
	s_cselect_b32 s79, 20, 21
	s_cselect_b32 s80, s69, s26
	s_cselect_b32 s81, s70, s27
	s_cselect_b32 s82, s40, s38
	s_cselect_b32 s83, s41, s39
	s_cselect_b32 s84, 32, 0
	s_cselect_b32 s85, s75, 0
	s_sub_i32 s76, s76, s84
	s_lshl_b32 s76, s76, 6
	s_lshl_b32 s85, s85, 10
	s_add_u32 s80, s80, s85
	s_addc_u32 s81, s81, 0
	s_add_u32 s80, s80, s76
	s_addc_u32 s81, s81, 0
	s_lshl_b32 s75, s75, s79
	s_add_u32 s82, s82, s75
	s_addc_u32 s83, s83, 0
	s_add_u32 s82, s82, s76
	s_addc_u32 s83, s83, 0
	v_mul_lo_u32 v1, s77, v235
	v_mul_lo_u32 v2, s78, v235
	v_or_b32_e32 v1, v1, v239
	v_or_b32_e32 v2, v2, v239
	v_lshlrev_b32_e32 v1, 1, v1
	v_lshlrev_b32_e32 v2, 1, v2
	v_lshl_add_u32 v3, s77, 7, v1
	v_lshl_add_u32 v188, s78, 7, v2
	s_waitcnt lgkmcnt(4)
	v_mfma_f32_16x16x32_bf16 v[160:163], v[164:167], v[168:171], v[160:163]
	s_waitcnt lgkmcnt(3)
	v_mfma_f32_16x16x32_bf16 v[156:159], v[164:167], v[172:175], v[156:159]
	s_waitcnt lgkmcnt(1)
	v_mfma_f32_16x16x32_bf16 v[152:155], v[164:167], v[180:183], v[152:155]
	s_waitcnt lgkmcnt(0)
	v_mfma_f32_16x16x32_bf16 v[148:151], v[164:167], v[184:187], v[148:151]
	ds_read_b128 v[164:167], v237 offset:2048
	v_mfma_f32_16x16x32_bf16 v[144:147], v[176:179], v[168:171], v[144:147]
	s_waitcnt vmcnt(7)
	ds_write_b128 v236, v[68:71] offset:16384
	global_load_dwordx4 v[68:71], v1, s[80:81]
	v_mfma_f32_16x16x32_bf16 v[140:143], v[176:179], v[172:175], v[140:143]
	s_waitcnt vmcnt(7)
	ds_write_b128 v236, v[72:75] offset:20480
	global_load_dwordx4 v[72:75], v3, s[80:81]
	v_mfma_f32_16x16x32_bf16 v[136:139], v[176:179], v[180:183], v[136:139]
	s_waitcnt vmcnt(7)
	ds_write_b128 v236, v[84:87] offset:24576
	global_load_dwordx4 v[84:87], v2, s[82:83]
	v_mfma_f32_16x16x32_bf16 v[132:135], v[176:179], v[184:187], v[132:135]
	s_waitcnt vmcnt(7)
	ds_write_b128 v236, v[92:95] offset:28672
	global_load_dwordx4 v[92:95], v188, s[82:83]
	ds_read_b128 v[176:179], v237 offset:3072
	s_waitcnt lgkmcnt(5)
	v_mfma_f32_16x16x32_bf16 v[128:131], v[164:167], v[168:171], v[128:131]
	v_mfma_f32_16x16x32_bf16 v[124:127], v[164:167], v[172:175], v[124:127]
	v_mfma_f32_16x16x32_bf16 v[120:123], v[164:167], v[180:183], v[120:123]
	v_mfma_f32_16x16x32_bf16 v[116:119], v[164:167], v[184:187], v[116:119]
	s_waitcnt lgkmcnt(0)
	v_mfma_f32_16x16x32_bf16 v[112:115], v[176:179], v[168:171], v[112:115]
	v_mfma_f32_16x16x32_bf16 v[108:111], v[176:179], v[172:175], v[108:111]
	v_mfma_f32_16x16x32_bf16 v[100:103], v[176:179], v[180:183], v[100:103]
	v_mfma_f32_16x16x32_bf16 v[104:107], v[176:179], v[184:187], v[104:107]
	s_waitcnt lgkmcnt(0)
	s_barrier
	ds_read_b128 v[164:167], v237 offset:16384
	ds_read_b128 v[176:179], v237 offset:17408
	ds_read_b128 v[168:171], v238 offset:24576
	ds_read_b128 v[172:175], v238 offset:25600
	ds_read_b128 v[180:183], v238 offset:26624
	ds_read_b128 v[184:187], v238 offset:27648
	s_waitcnt lgkmcnt(3)
	v_mfma_f32_16x16x32_bf16 v[160:163], v[164:167], v[168:171], v[160:163]
	s_min_u32 s12, s68, 0x8b
	s_add_i32 s12, s12, 4
	s_mul_i32 s13, s12, 0xab
	s_waitcnt lgkmcnt(2)
	v_mfma_f32_16x16x32_bf16 v[156:159], v[164:167], v[172:175], v[156:159]
	s_bfe_u32 s71, s13, 0x3000d
	s_mul_i32 s20, s71, 0xffffffd0
	s_add_i32 s20, s20, s12
	s_waitcnt lgkmcnt(1)
	v_mfma_f32_16x16x32_bf16 v[152:155], v[164:167], v[180:183], v[152:155]
	s_mov_b64 s[16:17], -1
	s_cmp_gt_i32 s20, 31
	s_waitcnt lgkmcnt(0)
	v_mfma_f32_16x16x32_bf16 v[148:151], v[164:167], v[184:187], v[148:151]
	ds_read_b128 v[164:167], v237 offset:18432
	v_mfma_f32_16x16x32_bf16 v[144:147], v[176:179], v[168:171], v[144:147]
	v_mfma_f32_16x16x32_bf16 v[140:143], v[176:179], v[172:175], v[140:143]
	v_mfma_f32_16x16x32_bf16 v[136:139], v[176:179], v[180:183], v[136:139]
	v_mfma_f32_16x16x32_bf16 v[132:135], v[176:179], v[184:187], v[132:135]
	ds_read_b128 v[176:179], v237 offset:19456
	s_waitcnt vmcnt(7)
	ds_write_b128 v236, v[76:79]
	s_waitcnt vmcnt(6)
	ds_write_b128 v236, v[80:83] offset:4096
	s_waitcnt lgkmcnt(3)
	v_mfma_f32_16x16x32_bf16 v[128:131], v[164:167], v[168:171], v[128:131]
	s_waitcnt vmcnt(5)
	ds_write_b128 v236, v[88:91] offset:8192
	s_waitcnt vmcnt(4)
	ds_write_b128 v236, v[96:99] offset:12288
	v_mfma_f32_16x16x32_bf16 v[124:127], v[164:167], v[172:175], v[124:127]
	v_mfma_f32_16x16x32_bf16 v[120:123], v[164:167], v[180:183], v[120:123]
	v_mfma_f32_16x16x32_bf16 v[116:119], v[164:167], v[184:187], v[116:119]
	s_waitcnt lgkmcnt(4)
	v_mfma_f32_16x16x32_bf16 v[112:115], v[176:179], v[168:171], v[112:115]
	v_mfma_f32_16x16x32_bf16 v[108:111], v[176:179], v[172:175], v[108:111]
	v_mfma_f32_16x16x32_bf16 v[100:103], v[176:179], v[180:183], v[100:103]
	v_mfma_f32_16x16x32_bf16 v[104:107], v[176:179], v[184:187], v[104:107]
	s_cbranch_scc0 .LBB0_588
	s_lshl_b32 s12, s71, 10
	s_add_u32 s14, s69, s12
	s_addc_u32 s15, s70, 0
	s_lshl_b32 s12, s20, 5
	s_add_i32 s22, s12, 0xfffffc00
	s_lshl_b64 s[12:13], s[22:23], 1
	s_add_u32 s12, s14, s12
	s_addc_u32 s13, s15, s13
	s_mov_b64 s[16:17], 0
	s_mov_b64 s[14:15], s[22:23]

; template <typename SrcF, typename PostF>
; __device__ __forceinline__ void gemm_stream32(const int nt, SrcF src32, PostF post32, f32x4 (&acc)[4][4], char* smem) {
;     ...
;   __syncthreads();
;   G_LOAD(g0, 0);
;   G_LOAD(g1, 1);
;   G_WRITE(g0, 0);
;   G_LOAD(g0, 2);
;   __syncthreads();
; __device__ void phase_merge(const Params& p, int layer, char* smem) {
;     ...
;   for (int t = li_; t < rbp_ * 8; t += nl_) {
;     const int rg_ = t / (8 * 8), v_ = t % (8 * 8);
;     const int rb = xg_ * rbp_ + rg_ * 8 + (v_ & 7), cb = v_ >> 3;
;     f32x4 mg[4][4], acc[4][4];
; #pragma unroll
;     for (int m = 0; m < 4; ++m)
; #pragma unroll
;       for (int n = 0; n < 4; ++n) {
;         mg[m][n] = f32x4{0.f, 0.f, 0.f, 0.f};
;         acc[m][n] = f32x4{0.f, 0.f, 0.f, 0.f};
;       }
;     const u16* Hb = H + (size_t)rb * 128 * 1024;
;     const u16* Wg = Wt + (size_t)(NP + cb * 128) * 1024;
;     const u16* Yb = Y + (size_t)rb * 128 * YW;
;     const u16* Wb = Wbr + (size_t)(cb * 128) * 512;
;     const float* bmp = p.b_merge + (size_t)layer * 3072 + cb * 128 + wc * 64 + fr;
.LBB0_1221:
	s_ashr_i32 s6, s52, 31
	s_lshr_b32 s6, s6, 26
	s_add_i32 s6, s52, s6
	s_ashr_i32 s7, s6, 6
	s_andn2_b32 s6, s6, 63
	s_sub_i32 s10, s52, s6
	s_lshl_b32 s6, s7, 3
	s_and_b32 s7, s10, 7
	s_add_i32 s6, s6, s46
	s_add_i32 s6, s6, s7
	s_ashr_i32 s7, s6, 31
	v_mov_b32_e32 v36, v232
	s_lshl_b64 s[16:17], s[6:7], 17
	s_lshl_b64 s[8:9], s[6:7], 18
	s_add_u32 s20, s36, s8
	v_lshrrev_b32_e32 v1, 4, v36
	v_lshrrev_b32_e32 v2, 5, v36
	v_xor_b32_e32 v1, v1, v2
	s_addc_u32 s21, s37, s9
	s_lshl_b32 s7, s10, 4
	v_lshlrev_b32_e32 v1, 1, v1
	s_and_b32 s22, s7, 0xffffff80
	v_ashrrev_i32_e32 v235, 2, v36
	v_and_b32_e32 v37, 3, v36
	v_bfe_u32 v3, v36, 5, 1
	v_and_b32_e32 v1, 2, v1
	s_add_i32 s14, s22, 0x1300
	v_bitop3_b32 v38, v1, v37, v3 bitop3:0x36
	v_lshlrev_b32_e32 v1, 11, v235
	s_lshl_b64 s[8:9], s[14:15], 11
	v_lshl_or_b32 v39, v38, 4, v1
	s_add_u32 s24, s38, s8
	v_add_u32_e32 v40, 0x20000, v39
	s_addc_u32 s25, s39, s9
	s_barrier
	global_load_dwordx4 v[20:23], v39, s[20:21]
	global_load_dwordx4 v[24:27], v40, s[20:21]
	global_load_dwordx4 v[28:31], v39, s[24:25]
	global_load_dwordx4 v[32:35], v40, s[24:25]
	global_load_dwordx4 v[68:71], v39, s[20:21] offset:64
	global_load_dwordx4 v[72:75], v40, s[20:21] offset:64
	global_load_dwordx4 v[84:87], v39, s[24:25] offset:64
	global_load_dwordx4 v[92:95], v40, s[24:25] offset:64
	global_load_dwordx4 v[76:79], v39, s[20:21] offset:128
	global_load_dwordx4 v[80:83], v40, s[20:21] offset:128
	global_load_dwordx4 v[88:91], v39, s[24:25] offset:128
	global_load_dwordx4 v[96:99], v40, s[24:25] offset:128
	v_lshrrev_b32_e32 v42, 2, v36
	v_bfe_u32 v43, v36, 3, 1
	s_mul_hi_i32 s7, s6, 0x60000
	s_mul_i32 s6, s6, 0x60000
	v_and_b32_e32 v41, 15, v36
	v_lshrrev_b32_e32 v45, 1, v36
	v_lshlrev_b32_e32 v37, 4, v37
	v_bitop3_b32 v42, v42, v43, 1 bitop3:0x6c
	s_add_u32 s55, s42, s6
	v_and_b32_e32 v44, 48, v36
	v_lshlrev_b32_e32 v43, 4, v43
	v_and_or_b32 v41, v45, s47, v41
	v_lshl_or_b32 v236, v235, 6, v37
	v_lshlrev_b32_e32 v37, 5, v42
	s_addc_u32 s63, s43, s7
	s_ashr_i32 s23, s22, 31
	v_mov_b32_e32 v2, v0
	v_mov_b32_e32 v3, v0
	v_mov_b32_e32 v6, v0
	v_mov_b32_e32 v7, v0
	v_lshlrev_b32_e32 v36, 6, v36
	v_lshlrev_b32_e32 v41, 6, v41
	v_or_b32_e32 v42, v37, v43
	v_bitop3_b32 v37, v37, v44, v43 bitop3:0x36
	s_lshl_b64 s[6:7], s[22:23], 10
	v_mov_b32_e32 v1, v0
	v_mov_b32_e32 v4, v0
	v_mov_b32_e32 v5, v0
	v_mov_b32_e32 v100, 0
	v_mov_b64_e32 v[10:11], v[6:7]
	v_mov_b64_e32 v[14:15], v[6:7]
	v_mov_b64_e32 v[18:19], v[6:7]
	v_bitop3_b32 v237, v42, v41, v44 bitop3:0xde
	v_and_or_b32 v238, v36, s48, v37
	v_lshlrev_b32_e32 v239, 3, v38
	s_add_u32 s26, s40, s6
	v_mov_b64_e32 v[38:39], v[6:7]
	v_mov_b64_e32 v[42:43], v[6:7]
	v_mov_b64_e32 v[46:47], v[6:7]
	v_mov_b64_e32 v[50:51], v[6:7]
	v_mov_b64_e32 v[54:55], v[6:7]
	v_mov_b64_e32 v[58:59], v[6:7]
	v_mov_b64_e32 v[62:63], v[6:7]
	v_mov_b64_e32 v[66:67], v[6:7]
	v_mov_b64_e32 v[106:107], v[2:3]
	s_mov_b32 s53, 1
	s_mov_b32 s54, -2
	v_mov_b64_e32 v[8:9], v[4:5]
	v_mov_b64_e32 v[12:13], v[4:5]
	v_mov_b64_e32 v[16:17], v[4:5]
	v_lshl_add_u64 v[230:231], s[22:23], 2, v[228:229]
	s_addc_u32 s27, s41, s7
	v_mov_b64_e32 v[36:37], v[4:5]
	s_waitcnt vmcnt(11)
	ds_write_b128 v236, v[20:23]
	s_waitcnt vmcnt(10)
	ds_write_b128 v236, v[24:27] offset:4096
	s_waitcnt vmcnt(9)
	ds_write_b128 v236, v[28:31] offset:8192
	s_waitcnt vmcnt(8)
	ds_write_b128 v236, v[32:35] offset:12288
	v_mov_b64_e32 v[22:23], v[6:7]
	v_mov_b64_e32 v[26:27], v[6:7]
	v_mov_b64_e32 v[30:31], v[6:7]
	v_mov_b64_e32 v[34:35], v[6:7]
	v_mov_b64_e32 v[20:21], v[4:5]
	v_mov_b64_e32 v[24:25], v[4:5]
	v_mov_b64_e32 v[28:29], v[4:5]
	v_mov_b64_e32 v[32:33], v[4:5]
	v_mov_b64_e32 v[40:41], v[4:5]
	v_mov_b64_e32 v[44:45], v[4:5]
	v_mov_b64_e32 v[48:49], v[4:5]
	v_mov_b64_e32 v[52:53], v[4:5]
	v_mov_b64_e32 v[56:57], v[4:5]
	v_mov_b64_e32 v[60:61], v[4:5]
	v_mov_b64_e32 v[64:65], v[4:5]
	v_mov_b64_e32 v[104:105], v[0:1]
	v_mov_b32_e32 v101, v100
	v_mov_b32_e32 v102, v100
	v_mov_b32_e32 v103, v100
	v_mov_b32_e32 v108, v100
	v_mov_b32_e32 v109, v100
	v_mov_b32_e32 v110, v100
	v_mov_b32_e32 v111, v100
	v_mov_b32_e32 v112, v100
	v_mov_b32_e32 v113, v100
	v_mov_b32_e32 v114, v100
	v_mov_b32_e32 v115, v100
	v_mov_b32_e32 v116, v100
	v_mov_b32_e32 v117, v100
	v_mov_b32_e32 v118, v100
	v_mov_b32_e32 v119, v100
	v_mov_b32_e32 v120, v100
	v_mov_b32_e32 v121, v100
	v_mov_b32_e32 v122, v100
	v_mov_b32_e32 v123, v100
	v_mov_b32_e32 v124, v100
	v_mov_b32_e32 v125, v100
	v_mov_b32_e32 v126, v100
	v_mov_b32_e32 v127, v100
	v_mov_b32_e32 v128, v100
	v_mov_b32_e32 v129, v100
	v_mov_b32_e32 v130, v100
	v_mov_b32_e32 v131, v100
	v_mov_b32_e32 v132, v100
	v_mov_b32_e32 v133, v100
	v_mov_b32_e32 v134, v100
	v_mov_b32_e32 v135, v100
	v_mov_b32_e32 v136, v100
	v_mov_b32_e32 v137, v100
	v_mov_b32_e32 v138, v100
	v_mov_b32_e32 v139, v100
	v_mov_b32_e32 v140, v100
	v_mov_b32_e32 v141, v100
	v_mov_b32_e32 v142, v100
	v_mov_b32_e32 v143, v100
	v_mov_b32_e32 v144, v100
	v_mov_b32_e32 v145, v100
	v_mov_b32_e32 v146, v100
	v_mov_b32_e32 v147, v100
	v_mov_b32_e32 v148, v100
	v_mov_b32_e32 v149, v100
	v_mov_b32_e32 v150, v100
	v_mov_b32_e32 v151, v100
	v_mov_b32_e32 v152, v100
	v_mov_b32_e32 v153, v100
	v_mov_b32_e32 v154, v100
	v_mov_b32_e32 v155, v100
	v_mov_b32_e32 v156, v100
	v_mov_b32_e32 v157, v100
	v_mov_b32_e32 v158, v100
	v_mov_b32_e32 v159, v100
	v_mov_b32_e32 v160, v100
	v_mov_b32_e32 v161, v100
	v_mov_b32_e32 v162, v100
	v_mov_b32_e32 v163, v100
	s_waitcnt lgkmcnt(0)
	s_barrier
	s_branch .LBB0_1223

.LBB0_1223:
	ds_read_b128 v[164:167], v237
	ds_read_b128 v[168:171], v238 offset:8192
	ds_read_b128 v[172:175], v238 offset:9216
	ds_read_b128 v[176:179], v237 offset:1024
	ds_read_b128 v[180:183], v238 offset:10240
	ds_read_b128 v[184:187], v238 offset:11264
	s_add_i32 s54, s54, 2
	s_min_u32 s74, s54, 0x8c
	s_add_i32 s74, s74, 3
	s_mul_i32 s75, s74, 0xab
	s_bfe_u32 s75, s75, 0x3000d
	s_mul_i32 s76, s75, 0xffffffd0
	s_add_i32 s76, s76, s74
	s_movk_i32 s77, 0x400
	s_movk_i32 s78, 0x400
	s_cmp_gt_i32 s76, 31
	s_cselect_b32 s77, 0x600, s77
	s_cselect_b32 s78, 0x200, s78
	s_cselect_b32 s79, 20, 21
	s_cselect_b32 s80, s55, s20
	s_cselect_b32 s81, s63, s21
	s_cselect_b32 s82, s26, s24
	s_cselect_b32 s83, s27, s25
	s_cselect_b32 s84, 32, 0
	s_cselect_b32 s85, s75, 0
	s_sub_i32 s76, s76, s84
	s_lshl_b32 s76, s76, 6
	s_lshl_b32 s85, s85, 10
	s_add_u32 s80, s80, s85
	s_addc_u32 s81, s81, 0
	s_add_u32 s80, s80, s76
	s_addc_u32 s81, s81, 0
	s_lshl_b32 s75, s75, s79
	s_add_u32 s82, s82, s75
	s_addc_u32 s83, s83, 0
	s_add_u32 s82, s82, s76
	s_addc_u32 s83, s83, 0
	v_mul_lo_u32 v1, s77, v235
	v_mul_lo_u32 v2, s78, v235
	v_or_b32_e32 v1, v1, v239
	v_or_b32_e32 v2, v2, v239
	v_lshlrev_b32_e32 v1, 1, v1
	v_lshlrev_b32_e32 v2, 1, v2
	v_lshl_add_u32 v3, s77, 7, v1
	v_lshl_add_u32 v188, s78, 7, v2
	s_waitcnt lgkmcnt(4)
	v_mfma_f32_16x16x32_bf16 v[160:163], v[164:167], v[168:171], v[160:163]
	s_waitcnt lgkmcnt(3)
	v_mfma_f32_16x16x32_bf16 v[156:159], v[164:167], v[172:175], v[156:159]
	s_waitcnt lgkmcnt(1)
	v_mfma_f32_16x16x32_bf16 v[152:155], v[164:167], v[180:183], v[152:155]
	s_waitcnt lgkmcnt(0)
	v_mfma_f32_16x16x32_bf16 v[148:151], v[164:167], v[184:187], v[148:151]
	ds_read_b128 v[164:167], v237 offset:2048
	v_mfma_f32_16x16x32_bf16 v[144:147], v[176:179], v[168:171], v[144:147]
	s_waitcnt vmcnt(7)
	ds_write_b128 v236, v[68:71] offset:16384
	global_load_dwordx4 v[68:71], v1, s[80:81]
	v_mfma_f32_16x16x32_bf16 v[140:143], v[176:179], v[172:175], v[140:143]
	s_waitcnt vmcnt(7)
	ds_write_b128 v236, v[72:75] offset:20480
	global_load_dwordx4 v[72:75], v3, s[80:81]
	v_mfma_f32_16x16x32_bf16 v[136:139], v[176:179], v[180:183], v[136:139]
	s_waitcnt vmcnt(7)
	ds_write_b128 v236, v[84:87] offset:24576
	global_load_dwordx4 v[84:87], v2, s[82:83]
	v_mfma_f32_16x16x32_bf16 v[132:135], v[176:179], v[184:187], v[132:135]
	s_waitcnt vmcnt(7)
	ds_write_b128 v236, v[92:95] offset:28672
	global_load_dwordx4 v[92:95], v188, s[82:83]
	ds_read_b128 v[176:179], v237 offset:3072
	s_waitcnt lgkmcnt(5)
	v_mfma_f32_16x16x32_bf16 v[128:131], v[164:167], v[168:171], v[128:131]
	v_mfma_f32_16x16x32_bf16 v[124:127], v[164:167], v[172:175], v[124:127]
	v_mfma_f32_16x16x32_bf16 v[120:123], v[164:167], v[180:183], v[120:123]
	v_mfma_f32_16x16x32_bf16 v[116:119], v[164:167], v[184:187], v[116:119]
	s_waitcnt lgkmcnt(0)
	v_mfma_f32_16x16x32_bf16 v[112:115], v[176:179], v[168:171], v[112:115]
	v_mfma_f32_16x16x32_bf16 v[108:111], v[176:179], v[172:175], v[108:111]
	v_mfma_f32_16x16x32_bf16 v[100:103], v[176:179], v[180:183], v[100:103]
	v_mfma_f32_16x16x32_bf16 v[104:107], v[176:179], v[184:187], v[104:107]
	s_waitcnt lgkmcnt(0)
	s_barrier
	ds_read_b128 v[164:167], v237 offset:16384
	ds_read_b128 v[176:179], v237 offset:17408
	ds_read_b128 v[168:171], v238 offset:24576
	ds_read_b128 v[172:175], v238 offset:25600
	ds_read_b128 v[180:183], v238 offset:26624
	ds_read_b128 v[184:187], v238 offset:27648
	s_waitcnt lgkmcnt(3)
	v_mfma_f32_16x16x32_bf16 v[160:163], v[164:167], v[168:171], v[160:163]
	s_min_u32 s6, s54, 0x8b
	s_add_i32 s6, s6, 4
	s_mul_i32 s7, s6, 0xab
	s_waitcnt lgkmcnt(2)
	v_mfma_f32_16x16x32_bf16 v[156:159], v[164:167], v[172:175], v[156:159]
	s_bfe_u32 s64, s7, 0x3000d
	s_mul_i32 s12, s64, 0xffffffd0
	s_add_i32 s12, s12, s6
	s_waitcnt lgkmcnt(1)
	v_mfma_f32_16x16x32_bf16 v[152:155], v[164:167], v[180:183], v[152:155]
	s_mov_b64 s[10:11], -1
	s_cmp_gt_i32 s12, 31
	s_waitcnt lgkmcnt(0)
	v_mfma_f32_16x16x32_bf16 v[148:151], v[164:167], v[184:187], v[148:151]
	ds_read_b128 v[164:167], v237 offset:18432
	v_mfma_f32_16x16x32_bf16 v[144:147], v[176:179], v[168:171], v[144:147]
	v_mfma_f32_16x16x32_bf16 v[140:143], v[176:179], v[172:175], v[140:143]
	v_mfma_f32_16x16x32_bf16 v[136:139], v[176:179], v[180:183], v[136:139]
	v_mfma_f32_16x16x32_bf16 v[132:135], v[176:179], v[184:187], v[132:135]
	ds_read_b128 v[176:179], v237 offset:19456
	s_waitcnt vmcnt(7)
	ds_write_b128 v236, v[76:79]
	s_waitcnt vmcnt(6)
	ds_write_b128 v236, v[80:83] offset:4096
	s_waitcnt lgkmcnt(3)
	v_mfma_f32_16x16x32_bf16 v[128:131], v[164:167], v[168:171], v[128:131]
	s_waitcnt vmcnt(5)
	ds_write_b128 v236, v[88:91] offset:8192
	s_waitcnt vmcnt(4)
	ds_write_b128 v236, v[96:99] offset:12288
	v_mfma_f32_16x16x32_bf16 v[124:127], v[164:167], v[172:175], v[124:127]
	v_mfma_f32_16x16x32_bf16 v[120:123], v[164:167], v[180:183], v[120:123]
	v_mfma_f32_16x16x32_bf16 v[116:119], v[164:167], v[184:187], v[116:119]
	s_waitcnt lgkmcnt(4)
	v_mfma_f32_16x16x32_bf16 v[112:115], v[176:179], v[168:171], v[112:115]
	v_mfma_f32_16x16x32_bf16 v[108:111], v[176:179], v[172:175], v[108:111]
	v_mfma_f32_16x16x32_bf16 v[100:103], v[176:179], v[180:183], v[100:103]
	v_mfma_f32_16x16x32_bf16 v[104:107], v[176:179], v[184:187], v[104:107]
	s_cbranch_scc0 .LBB0_1230
	s_lshl_b32 s6, s64, 10
	s_add_u32 s8, s55, s6
	s_addc_u32 s9, s63, 0
	s_lshl_b32 s6, s12, 5
	s_add_i32 s14, s6, 0xfffffc00
	s_lshl_b64 s[6:7], s[14:15], 1
	s_add_u32 s6, s8, s6
	s_addc_u32 s7, s9, s7
	s_mov_b64 s[10:11], 0
	s_mov_b64 s[8:9], s[14:15]
